# P0 transposes balanced: last 256 w_o items done by light P1 waves
# baseline (speedup 1.0000x reference)
; __device__ __forceinline__ void transpose_item(const float* W, int K, int N, bf16* WT, int mode, LAS float* scr, int item, int lane) { transpose_item_t<false>(W, K, N, WT, mode, scr, item, lane, nullptr, nullptr, nullptr, nullptr); }
; __global__ void __launch_bounds__(512, 2) hybrid_fwd(Args args) {
;     ...
;         for (int it = gw; it < I_1 + 2 * I_4 + I_A0 + I_O0; it += NGW) {
;             int r = it;
;             if (r < I_1) { transpose_item(w_ffn1_in, DM, NFF, W1, 1, scr, r, lane); continue; } r -= I_1;
;             if (r < I_4) { transpose_item(w_ffn1_out, DFF, DM, W2, 0, scr, r, lane); continue; } r -= I_4;
;             if (r < I_4) { transpose_item(w_ffn2_out, DFF, DM, W4, 0, scr, r, lane); continue; } r -= I_4;
;             if (r < I_A0) { transpose_item(w_attn_out, AW, DM, WA, 0, scr, r, lane); continue; } r -= I_A0;
;             transpose_item(w_o, DM, DM, WO, 0, scr, r, lane);
;         }
.LBB0_25:
	s_lshl_b32 s90, s42, 3
	s_add_u32 s22, s86, 0x100000
	s_addc_u32 s23, s87, 0
	s_add_u32 s92, s86, 0xd00000
	s_addc_u32 s93, s87, 0
	v_writelane_b32 v252, s14, 3
	s_load_dwordx16 s[60:75], s[0:1], 0x0
	s_load_dwordx16 s[44:59], s[0:1], 0x40
	s_add_u32 s0, s86, 0x2300000
	v_writelane_b32 v252, s15, 4
	s_addc_u32 s1, s87, 0
	v_writelane_b32 v252, s0, 5
	v_and_b32_e32 v160, 63, v226
	s_nop 0
	v_writelane_b32 v252, s1, 6
	s_add_u32 s0, s86, 0x2500000
	s_addc_u32 s1, s87, 0
	v_writelane_b32 v252, s0, 7
	s_nop 1
	v_writelane_b32 v252, s1, 8
	s_add_u32 s0, s86, 0x3d00000
	s_addc_u32 s1, s87, 0
	v_writelane_b32 v252, s0, 9
	s_lshr_b32 s3, s95, 6
	s_mov_b32 s91, s3
	v_writelane_b32 v252, s1, 10
	s_lshl_b32 s0, s2, 3
	s_add_i32 s94, s3, s0
	s_add_u32 s88, s86, 0x200000
	s_addc_u32 s89, s87, 0
	s_cmp_lt_i32 s6, 1
	s_cselect_b64 s[0:1], -1, 0
	s_cmp_gt_i32 s7, 0
	s_cselect_b64 s[4:5], -1, 0
	s_and_b64 s[0:1], s[0:1], s[4:5]
	v_writelane_b32 v252, s0, 11
	s_andn2_b64 vcc, exec, s[0:1]
	s_nop 0
	v_writelane_b32 v252, s1, 12
	s_cbranch_vccnz .LBB0_45
	s_mov_b32 s98, 0
	s_lshl_b32 s0, s3, 14
	s_add_i32 s3, s0, 0
	s_cmpk_gt_i32 s94, 0x18ff
	s_cbranch_scc1 .LBB0_46
.Lp0_pre:
	v_ashrrev_i32_e32 v20, 5, v160
	v_lshlrev_b32_e32 v0, 2, v160
	s_movk_i32 s0, 0x84
	v_and_b32_e32 v16, 0x7c, v0
	v_mul_lo_u32 v2, v20, s0
	v_add3_u32 v21, s3, v16, v2
	v_lshlrev_b32_e32 v2, 3, v160
	v_mov_b32_e32 v17, 0
	v_and_b32_e32 v2, 56, v2
	v_readlane_b32 s0, v252, 7
	v_lshlrev_b32_e32 v18, 1, v2
	v_mov_b32_e32 v19, v17
	v_readlane_b32 s1, v252, 8
	v_mul_u32_u24_e32 v4, 0x84, v2
	v_ashrrev_i32_e32 v22, 3, v160
	v_lshl_add_u64 v[2:3], s[0:1], 0, v[18:19]
	v_readlane_b32 s0, v252, 5
	v_readlane_b32 s1, v252, 6
	v_lshlrev_b32_e32 v5, 2, v22
	v_lshl_add_u64 v[0:1], s[76:77], 0, v[16:17]
	v_lshl_add_u64 v[6:7], s[0:1], 0, v[18:19]
	v_readlane_b32 s0, v252, 9
	v_readlane_b32 s1, v252, 10
	v_add3_u32 v23, s3, v4, v5
	v_add_u32_e32 v24, 8, v22
	v_lshl_add_u64 v[10:11], s[0:1], 0, v[18:19]
	s_lshl_b32 s0, s2, 8
	s_lshl_b32 s1, s91, 5
	s_add_i32 s8, s0, s1
	s_lshl_b32 s0, s2, 4
	s_lshl_b32 s1, s91, 1
	s_add_i32 s0, s0, s1
	v_add_u32_e32 v25, 16, v22
	v_add_u32_e32 v26, 24, v22
	s_waitcnt lgkmcnt(0)
	v_lshl_add_u64 v[4:5], s[52:53], 0, v[16:17]
	v_lshl_add_u64 v[8:9], s[82:83], 0, v[16:17]
	v_lshl_add_u64 v[12:13], s[72:73], 0, v[16:17]
	v_lshl_add_u64 v[14:15], s[92:93], 0, v[18:19]
	v_lshl_add_u64 v[16:17], s[70:71], 0, v[16:17]
	v_lshl_add_u64 v[18:19], s[88:89], 0, v[18:19]
	s_lshl_b32 s9, s42, 8
	s_add_i32 s10, s0, 0x1d200
	s_lshl_b32 s11, s42, 4
	s_mov_b32 s1, 0
	s_movk_i32 s12, 0x7fff
	s_mov_b32 s13, 0xffff0000
	s_movk_i32 s14, 0x1600
	s_movk_i32 s15, 0x5800
	v_add_u32_e32 v27, 0x400, v21
	v_add_u32_e32 v28, 0x800, v21
	v_add_u32_e32 v29, 0xc00, v21
	v_add_u32_e32 v30, 0x1000, v21
	v_add_u32_e32 v31, 0x1400, v21
	v_add_u32_e32 v32, 0x1800, v21
	v_add_u32_e32 v33, 0x1c00, v21
	v_mov_b32_e32 v34, 0x3f317218
	v_mov_b32_e32 v35, 0x3fb8aa3b
	s_mov_b32 s16, s94
	s_add_i32 s16, s16, s98
	s_lshl_b32 s4, s98, 5
	s_add_i32 s8, s8, s4
	s_lshl_b32 s4, s98, 1
	s_add_i32 s10, s10, s4
	s_branch .LBB0_29
.LBB0_28:
	s_add_i32 s16, s16, s90
	s_add_i32 s8, s8, s9
	s_add_i32 s10, s10, s11
	s_cmpk_gt_i32 s16, 0x1fff
	s_cbranch_scc1 .Lp1_wo_ret
	s_cmpk_gt_i32 s16, 0x17ff
	s_cbranch_scc1 .LBB0_46

; __device__ __forceinline__ void transpose_item(const float* W, int K, int N, bf16* WT, int mode, LAS float* scr, int item, int lane) { transpose_item_t<false>(W, K, N, WT, mode, scr, item, lane, nullptr, nullptr, nullptr, nullptr); }
; __global__ void __launch_bounds__(512, 2) hybrid_fwd(Args args) {
;     ...
;         for (int it = gw; it < I_1 + 2 * I_4 + I_A0 + I_O0; it += NGW) {
;             int r = it;
;             if (r < I_1) { transpose_item(w_ffn1_in, DM, NFF, W1, 1, scr, r, lane); continue; } r -= I_1;
;             if (r < I_4) { transpose_item(w_ffn1_out, DFF, DM, W2, 0, scr, r, lane); continue; } r -= I_4;
;             if (r < I_4) { transpose_item(w_ffn2_out, DFF, DM, W4, 0, scr, r, lane); continue; } r -= I_4;
;             if (r < I_A0) { transpose_item(w_attn_out, AW, DM, WA, 0, scr, r, lane); continue; } r -= I_A0;
;             transpose_item(w_o, DM, DM, WO, 0, scr, r, lane);
;         }
;     ...
;         for (int it = gw; it < 2 * I_1; it += NGW) { const int bb = it >= I_1 ? 1 : 0; const float* mb = mod + bb * NADA;
;             transpose_item_t<true>(w_ffn2_in, DM, NFF, W3 + (size_t)bb * NFF * DM, 1, scr, it - bb * I_1, lane, g_ffn2, mb + 7 * DM, mb + 6 * DM, BIASP + (size_t)bb * 16 * NBIAS + NIN); }
.LBB0_130:
	s_lshl_b32 s94, s2, 3
	s_add_i32 s94, s94, s96
	s_sub_i32 s0, s94, 0x600
	s_cmp_lt_u32 s0, 0x100
	s_cbranch_scc0 .Lp1_wo_skip
	v_writelane_b32 v252, s10, 13
	v_writelane_b32 v252, s11, 14
	v_writelane_b32 v252, s12, 15
	v_writelane_b32 v252, s13, 16
	s_mov_b32 s91, s96
	s_lshl_b32 s3, s96, 14
	s_movk_i32 s98, 0x1200
	s_branch .Lp0_pre
.Lp1_wo_ret:
	v_readlane_b32 s10, v252, 13
	v_readlane_b32 s11, v252, 14
	v_readlane_b32 s12, v252, 15
	v_readlane_b32 s13, v252, 16
